# single early buffer_wbl2 per XCD at 50 percent arrival
# speedup vs baseline: 1.0033x; 1.0033x over previous
; __device__ __forceinline__ unsigned xb_ld(unsigned* p)              { return __hip_atomic_load(p, __ATOMIC_RELAXED, __HIP_MEMORY_SCOPE_AGENT); }
; __device__ __forceinline__ unsigned xb_add(unsigned* p, unsigned v) { return __hip_atomic_fetch_add(p, v, __ATOMIC_RELAXED, __HIP_MEMORY_SCOPE_AGENT); }
; #define XB_SPIN(cond, bar) do { unsigned _sp = 0; while (cond) { __builtin_amdgcn_s_sleep(0); \
;     if ((++_sp & 255u) == 0u) { if (xb_ld(&(bar)[XB_TMO])) break; if (_sp > XB_SPIN_CAP) { atomicAdd(&(bar)[XB_TMO], 1u); break; } } } } while (0)
; __device__ __forceinline__ void xcd_barrier(const XcdBarrier& b) {
;     ...
;         const unsigned old = xb_add(&bar[XB_XSUB(b.x)], 1u);
;         const unsigned gen = old / nloc;
;         if (old + 1u == (gen + 1u) * nloc) {
;             __builtin_amdgcn_fence(__ATOMIC_RELEASE, "agent");
;     ...
;             XB_SPIN(xb_ld(&bar[XB_XGEN(b.x)]) == gen, bar);
.LBB0_155:
	s_or_b64 exec, exec, s[0:1]
	v_cvt_f32_u32_e32 v4, v2
	s_waitcnt vmcnt(0)
	v_readfirstlane_b32 s0, v3
	v_sub_u32_e32 v3, 0, v2
	v_rcp_iflag_f32_e32 v4, v4
	v_add_u32_e32 v5, s0, v1
	v_mul_f32_e32 v4, 0x4f7ffffe, v4
	v_cvt_u32_f32_e32 v4, v4
	v_mul_lo_u32 v1, v3, v4
	v_mul_hi_u32 v1, v4, v1
	v_add_u32_e32 v1, v4, v1
	v_mul_hi_u32 v1, v5, v1
	v_mul_lo_u32 v3, v1, v2
	v_sub_u32_e32 v3, v5, v3
	v_add_u32_e32 v4, 1, v1
	v_cmp_ge_u32_e32 vcc, v3, v2
	s_nop 1
	v_cndmask_b32_e32 v1, v1, v4, vcc
	v_sub_u32_e32 v4, v3, v2
	v_cndmask_b32_e32 v3, v3, v4, vcc
	v_add_u32_e32 v4, 1, v1
	v_cmp_ge_u32_e32 vcc, v3, v2
	v_add_u32_e32 v3, 1, v5
	s_nop 0
	v_cndmask_b32_e32 v1, v1, v4, vcc
	v_mul_lo_u32 v4, v2, v1
	v_add_u32_e32 v2, v4, v2
	v_cmp_ne_u32_e32 vcc, v3, v2
	s_and_saveexec_b64 s[0:1], vcc
	s_xor_b64 s[0:1], exec, s[0:1]
	s_cbranch_execz .LBB0_169
	v_readlane_b32 s2, v252, 7
	v_readlane_b32 s3, v252, 8
	s_waitcnt lgkmcnt(0)
	v_mad_u32_u24 v1, v0, v1, v0
	v_sub_u32_e32 v3, v3, v4
	v_sub_u32_e32 v4, v2, v4
	v_lshlrev_b32_e32 v3, 1, v3
	v_cmp_eq_u32_e32 vcc, v3, v4
	s_cbranch_vccz .Lewb_skip0
	buffer_wbl2 sc1
